# cross-attention: first K/V tile loads issued at item start, before the Q fragment loads and conversion
# baseline (speedup 1.0000x reference)
; __device__ __forceinline__ u32x4 pack8(const float* f) { u32x4 o; o.x = pk2(f[0], f[1]); o.y = pk2(f[2], f[3]); o.z = pk2(f[4], f[5]); o.w = pk2(f[6], f[7]); return o; }
; __device__ __forceinline__ void phase_xattn(CArgs& A, int l, unsigned char* lds, int tid) {
;     ...
;     for (int it = blockIdx.x; it < BATCH * 4 * 16; it += gridDim.x) {
;         asm volatile("" : "+v"(tid));
;         const int wave = tid >> 6, lane = tid & 63, r = lane & 15, g = lane >> 4;
;         const int b = it >> 6, h = (it >> 4) & 3, qch = it & 15;
;         const size_t row = (size_t)b * SEQ + qch * 128 + wave * 16 + r;
;         bf16x8 qf[8];
; #pragma unroll
;         for (int ks = 0; ks < 8; ++ks) { float f[8]; unpack8(*(const u32x4*)(Q + row * DM + h * 256 + 32 * ks + 8 * g), f);
; #pragma unroll
;             for (int i = 0; i < 8; ++i) f[i] *= 0.0625f;
;             qf[ks] = __builtin_bit_cast(bf16x8, pack8(f)); }
;         f32x4 o[16];
; #pragma unroll
;         for (int i = 0; i < 16; ++i) o[i] = (f32x4){0.f, 0.f, 0.f, 0.f};
;         float m = -INFINITY, lsum = 0.f;
;         const int skey = tid >> 3, sdc = (tid & 7) * 32;
;         const bf16* kvbase = KV + ((size_t)b * NMEM + skey) * 4096 + l * 2048 + h * 256 + sdc;
;         u32x4 kr[4], vr[4];
; #pragma unroll
;         for (int i = 0; i < 4; ++i) { kr[i] = *(const u32x4*)(kvbase + i * 8); vr[i] = *(const u32x4*)(kvbase + 1024 + i * 8); }
.LBB0_144:
	s_ashr_i32 s4, s11, 6
	s_ashr_i32 s5, s4, 31
	s_lshl_b32 s8, s11, 7
	s_lshl_b64 s[0:1], s[4:5], 11
	s_and_b32 s8, s8, 0x780
	v_ashrrev_i32_e32 v2, 2, v1
	v_and_b32_e32 v36, 15, v1
	s_or_b32 s0, s0, s8
	v_and_b32_e32 v2, -16, v2
	v_ashrrev_i32_e32 v3, 31, v2
	v_or_b32_e32 v4, s0, v36
	v_mov_b32_e32 v5, s1
	v_lshl_add_u64 v[2:3], v[4:5], 0, v[2:3]
	s_lshl_b32 s0, s11, 4
	v_lshlrev_b64 v[144:145], 11, v[2:3]
	s_and_b32 s36, s0, 0x300
	v_bfe_u32 v37, v1, 4, 2
	v_lshl_add_u64 v[2:3], s[38:39], 0, v[144:145]
	s_lshl_b32 s14, s36, 1
	v_lshl_add_u64 v[2:3], v[2:3], 0, s[14:15]
	v_lshlrev_b32_e32 v34, 4, v37
	v_mov_b32_e32 v35, v0
	v_lshl_add_u64 v[22:23], v[2:3], 0, v[34:35]
	v_ashrrev_i32_e32 v204, 3, v1
	s_lshl_b64 s[98:99], s[4:5], 21
	v_ashrrev_i32_e32 v205, 31, v204
	s_add_u32 s98, s9, s98
	s_addc_u32 s99, s10, s99
	v_lshlrev_b64 v[206:207], 13, v[204:205]
	v_lshl_add_u64 v[208:209], s[98:99], 0, v[206:207]
	v_lshl_add_u64 v[208:209], s[40:41], 1, v[208:209]
	v_lshlrev_b32_e32 v206, 6, v1
	v_lshl_add_u64 v[208:209], v[208:209], 0, s[14:15]
	v_and_b32_e32 v206, 0x1c0, v206
	v_mov_b32_e32 v207, v0
	v_lshl_add_u64 v[208:209], v[208:209], 0, v[206:207]
	global_load_dwordx4 v[102:105], v[208:209], off offset:32
	global_load_dwordx4 v[106:109], v[208:209], off offset:16
	global_load_dwordx4 v[110:113], v[208:209], off
	global_load_dwordx4 v[114:117], v[208:209], off offset:2096
	global_load_dwordx4 v[118:121], v[208:209], off offset:2080
	global_load_dwordx4 v[122:125], v[208:209], off offset:2064
	global_load_dwordx4 v[126:129], v[208:209], off offset:2048
	global_load_dwordx4 v[2:5], v[22:23], off
	global_load_dwordx4 v[6:9], v[22:23], off offset:64
	global_load_dwordx4 v[10:13], v[22:23], off offset:128
	global_load_dwordx4 v[14:17], v[22:23], off offset:192
	global_load_dwordx4 v[18:21], v[22:23], off offset:256
	s_mov_b32 s0, 0x3d800000
	v_mov_b32_e32 v147, v0
	v_cmp_lt_i32_e32 vcc, v178, v173
	v_lshlrev_b32_e32 v143, 2, v37
	v_and_b32_e32 v37, 7, v1
	v_lshlrev_b32_e32 v37, 6, v37
	v_mul_u32_u24_e32 v36, 0x220, v36
	v_mov_b32_e32 v130, 0
	v_mov_b32_e32 v156, 0xff800000
	s_mov_b64 s[44:45], 0
	v_mov_b32_e32 v51, v130
	s_waitcnt lgkmcnt(0)
	v_mov_b32_e32 v52, v130
	s_waitcnt lgkmcnt(2)
	v_mov_b32_e32 v53, v130
	v_mov_b32_e32 v54, 0
	v_mov_b32_e32 v55, v130
	s_waitcnt lgkmcnt(1)
	v_mov_b32_e32 v56, v130
	s_waitcnt lgkmcnt(0)
	v_mov_b32_e32 v57, v130
	v_mov_b32_e32 v58, 0
	v_mov_b32_e32 v59, v130
	v_mov_b32_e32 v60, v130
	v_mov_b32_e32 v61, v130
	v_mov_b32_e32 v74, 0
	v_mov_b32_e32 v75, v130
	v_mov_b32_e32 v76, v130
	v_mov_b32_e32 v77, v130
	s_waitcnt vmcnt(0)
	v_mov_b32_e32 v94, 0
	v_mov_b32_e32 v95, v130
	v_mov_b32_e32 v96, v130
	v_mov_b32_e32 v97, v130
	v_mov_b32_e32 v82, 0
	v_mov_b32_e32 v83, v130
	v_mov_b32_e32 v84, v130
	v_mov_b32_e32 v85, v130
	v_mov_b32_e32 v90, 0
	v_mov_b32_e32 v91, v130
	v_mov_b32_e32 v92, v130
	v_mov_b32_e32 v93, v130
	v_mov_b32_e32 v78, 0
	v_mov_b32_e32 v79, v130
	v_mov_b32_e32 v80, v130
	v_mov_b32_e32 v81, v130
	v_mov_b32_e32 v70, 0
	v_mov_b32_e32 v71, v130
	v_mov_b32_e32 v72, v130
	v_mov_b32_e32 v73, v130
	v_mov_b32_e32 v62, 0
	v_mov_b32_e32 v63, v130
	v_mov_b32_e32 v64, v130
	v_mov_b32_e32 v65, v130
	v_mov_b32_e32 v66, 0
	v_mov_b32_e32 v67, v130
	v_mov_b32_e32 v68, v130
	v_mov_b32_e32 v69, v130
	v_mov_b32_e32 v86, 0
	v_mov_b32_e32 v87, v130
	v_mov_b32_e32 v88, v130
	v_mov_b32_e32 v89, v130
	s_waitcnt vmcnt(4)
	v_lshlrev_b32_e32 v25, 16, v3
	v_lshlrev_b32_e32 v24, 16, v2
	v_and_b32_e32 v3, 0xffff0000, v3
	v_and_b32_e32 v2, 0xffff0000, v2
	v_lshlrev_b32_e32 v27, 16, v5
	v_lshlrev_b32_e32 v26, 16, v4
	v_and_b32_e32 v5, 0xffff0000, v5
	v_and_b32_e32 v4, 0xffff0000, v4
	s_waitcnt vmcnt(3)
	v_lshlrev_b32_e32 v29, 16, v7
	v_lshlrev_b32_e32 v28, 16, v6
	v_and_b32_e32 v7, 0xffff0000, v7
	v_and_b32_e32 v6, 0xffff0000, v6
	v_lshlrev_b32_e32 v31, 16, v9
	v_lshlrev_b32_e32 v30, 16, v8
	v_and_b32_e32 v9, 0xffff0000, v9
	v_and_b32_e32 v8, 0xffff0000, v8
	v_pk_mul_f32 v[24:25], v[24:25], s[0:1] op_sel_hi:[1,0]
	v_pk_mul_f32 v[2:3], v[2:3], s[0:1] op_sel_hi:[1,0]
	v_pk_mul_f32 v[26:27], v[26:27], s[0:1] op_sel_hi:[1,0]
	v_pk_mul_f32 v[4:5], v[4:5], s[0:1] op_sel_hi:[1,0]
	v_pk_mul_f32 v[28:29], v[28:29], s[0:1] op_sel_hi:[1,0]
	v_pk_mul_f32 v[6:7], v[6:7], s[0:1] op_sel_hi:[1,0]
	v_pk_mul_f32 v[30:31], v[30:31], s[0:1] op_sel_hi:[1,0]
	v_pk_mul_f32 v[8:9], v[8:9], s[0:1] op_sel_hi:[1,0]
	v_bfe_u32 v39, v24, 16, 1
	v_bfe_u32 v32, v5, 16, 1
	v_bfe_u32 v35, v3, 16, 1
	v_bfe_u32 v38, v2, 16, 1
	v_bfe_u32 v40, v25, 16, 1
	v_bfe_u32 v41, v26, 16, 1
	v_bfe_u32 v42, v27, 16, 1
	v_bfe_u32 v44, v8, 16, 1
	v_bfe_u32 v46, v6, 16, 1
	v_bfe_u32 v47, v28, 16, 1
	v_bfe_u32 v49, v30, 16, 1
	v_bfe_u32 v50, v31, 16, 1
	v_add3_u32 v24, v24, v39, s84
	v_bfe_u32 v33, v4, 16, 1
	v_bfe_u32 v43, v9, 16, 1
	v_bfe_u32 v45, v7, 16, 1
	v_bfe_u32 v48, v29, 16, 1
	v_add3_u32 v2, v2, v38, s84
	v_add3_u32 v3, v3, v35, s84
	v_add3_u32 v5, v5, v32, s84
	v_add3_u32 v27, v27, v42, s84
	v_add3_u32 v26, v26, v41, s84
	v_add3_u32 v25, v25, v40, s84
	v_add3_u32 v32, v6, v46, s84
	v_add3_u32 v35, v8, v44, s84
	v_add3_u32 v31, v31, v50, s84
	v_add3_u32 v6, v30, v49, s84
	v_add3_u32 v8, v28, v47, s84
	v_lshrrev_b32_e32 v24, 16, v24
	v_add3_u32 v4, v4, v33, s84
	v_add3_u32 v33, v7, v45, s84
	v_add3_u32 v38, v9, v43, s84
	v_add3_u32 v7, v29, v48, s84
	v_lshrrev_b32_e32 v25, 16, v25
	v_lshrrev_b32_e32 v26, 16, v26
	v_lshrrev_b32_e32 v9, 16, v27
	v_lshrrev_b32_e32 v27, 16, v8
	v_lshrrev_b32_e32 v29, 16, v6
	v_and_or_b32 v6, v2, s3, v24
	v_lshrrev_b32_e32 v2, 16, v31
	v_lshrrev_b32_e32 v28, 16, v7
	v_and_or_b32 v9, v5, s3, v9
	v_and_or_b32 v8, v4, s3, v26
	v_and_or_b32 v7, v3, s3, v25
	v_and_or_b32 v5, v38, s3, v2
	v_and_or_b32 v2, v32, s3, v27
	s_waitcnt vmcnt(2)
; __device__ __forceinline__ u32x4 pack8(const float* f) { u32x4 o; o.x = pk2(f[0], f[1]); o.y = pk2(f[2], f[3]); o.z = pk2(f[4], f[5]); o.w = pk2(f[6], f[7]); return o; }
; __device__ __forceinline__ void phase_xattn(CArgs& A, int l, unsigned char* lds, int tid) {
;     ...
;         for (int ks = 0; ks < 8; ++ks) { float f[8]; unpack8(*(const u32x4*)(Q + row * DM + h * 256 + 32 * ks + 8 * g), f);
; #pragma unroll
;             for (int i = 0; i < 8; ++i) f[i] *= 0.0625f;
;             qf[ks] = __builtin_bit_cast(bf16x8, pack8(f)); }
	v_lshlrev_b32_e32 v25, 16, v11
	v_lshlrev_b32_e32 v24, 16, v10
	v_and_b32_e32 v11, 0xffff0000, v11
	v_and_b32_e32 v10, 0xffff0000, v10
	v_lshlrev_b32_e32 v27, 16, v13
	v_lshlrev_b32_e32 v26, 16, v12
	v_and_b32_e32 v13, 0xffff0000, v13
	v_and_b32_e32 v12, 0xffff0000, v12
	v_pk_mul_f32 v[10:11], v[10:11], s[0:1] op_sel_hi:[1,0]
	v_pk_mul_f32 v[12:13], v[12:13], s[0:1] op_sel_hi:[1,0]
	v_and_or_b32 v4, v35, s3, v29
	v_and_or_b32 v3, v33, s3, v28
	v_pk_mul_f32 v[24:25], v[24:25], s[0:1] op_sel_hi:[1,0]
	v_pk_mul_f32 v[26:27], v[26:27], s[0:1] op_sel_hi:[1,0]
	v_bfe_u32 v28, v13, 16, 1
	v_bfe_u32 v29, v12, 16, 1
	v_bfe_u32 v30, v11, 16, 1
	v_bfe_u32 v31, v10, 16, 1
	v_add3_u32 v10, v10, v31, s84
	v_add3_u32 v11, v11, v30, s84
	v_add3_u32 v12, v12, v29, s84
	v_add3_u32 v13, v13, v28, s84
	v_bfe_u32 v28, v24, 16, 1
	v_bfe_u32 v29, v25, 16, 1
	v_bfe_u32 v30, v26, 16, 1
	v_bfe_u32 v31, v27, 16, 1
	v_add3_u32 v31, v27, v31, s84
	v_add3_u32 v26, v26, v30, s84
	v_add3_u32 v25, v25, v29, s84
	v_add3_u32 v24, v24, v28, s84
	v_lshrrev_b32_e32 v28, 16, v24
	v_lshrrev_b32_e32 v29, 16, v25
	v_lshrrev_b32_e32 v30, 16, v26
	global_load_dwordx4 v[24:27], v[22:23], off offset:320
	v_lshrrev_b32_e32 v31, 16, v31
	v_and_or_b32 v13, v13, s3, v31
	v_and_or_b32 v12, v12, s3, v30
	s_waitcnt vmcnt(2)
	v_lshlrev_b32_e32 v31, 16, v17
	v_lshlrev_b32_e32 v30, 16, v16
	v_and_b32_e32 v17, 0xffff0000, v17
	v_and_b32_e32 v16, 0xffff0000, v16
	v_and_or_b32 v11, v11, s3, v29
	v_and_or_b32 v10, v10, s3, v28
	v_lshlrev_b32_e32 v29, 16, v15
	v_lshlrev_b32_e32 v28, 16, v14
	v_and_b32_e32 v15, 0xffff0000, v15
	v_and_b32_e32 v14, 0xffff0000, v14
	v_pk_mul_f32 v[16:17], v[16:17], s[0:1] op_sel_hi:[1,0]
	v_pk_mul_f32 v[28:29], v[28:29], s[0:1] op_sel_hi:[1,0]
	v_pk_mul_f32 v[14:15], v[14:15], s[0:1] op_sel_hi:[1,0]
	v_bfe_u32 v32, v17, 16, 1
	v_bfe_u32 v33, v16, 16, 1
	v_pk_mul_f32 v[30:31], v[30:31], s[0:1] op_sel_hi:[1,0]
	v_bfe_u32 v35, v15, 16, 1
	v_bfe_u32 v38, v14, 16, 1
	v_add3_u32 v16, v16, v33, s84
	v_add3_u32 v17, v17, v32, s84
	v_bfe_u32 v32, v28, 16, 1
	v_bfe_u32 v33, v29, 16, 1
	v_add3_u32 v14, v14, v38, s84
	v_add3_u32 v15, v15, v35, s84
	v_bfe_u32 v35, v30, 16, 1
	v_bfe_u32 v38, v31, 16, 1
	v_add3_u32 v29, v29, v33, s84
	v_add3_u32 v28, v28, v32, s84
	v_add3_u32 v38, v31, v38, s84
	v_add3_u32 v35, v30, v35, s84
	v_lshrrev_b32_e32 v32, 16, v28
	v_lshrrev_b32_e32 v33, 16, v29
	global_load_dwordx4 v[28:31], v[22:23], off offset:384
	v_lshrrev_b32_e32 v38, 16, v38
	v_and_or_b32 v17, v17, s3, v38
	v_and_or_b32 v15, v15, s3, v33
	v_and_or_b32 v14, v14, s3, v32
	s_waitcnt vmcnt(2)
	v_lshlrev_b32_e32 v33, 16, v19
	v_lshlrev_b32_e32 v32, 16, v18
	v_and_b32_e32 v19, 0xffff0000, v19
	v_and_b32_e32 v18, 0xffff0000, v18
	v_lshlrev_b32_e32 v39, 16, v21
	v_lshlrev_b32_e32 v38, 16, v20
	v_and_b32_e32 v21, 0xffff0000, v21
	v_and_b32_e32 v20, 0xffff0000, v20
	v_pk_mul_f32 v[18:19], v[18:19], s[0:1] op_sel_hi:[1,0]
	v_pk_mul_f32 v[20:21], v[20:21], s[0:1] op_sel_hi:[1,0]
	v_pk_mul_f32 v[32:33], v[32:33], s[0:1] op_sel_hi:[1,0]
	v_pk_mul_f32 v[38:39], v[38:39], s[0:1] op_sel_hi:[1,0]
	v_bfe_u32 v40, v20, 16, 1
	v_bfe_u32 v41, v19, 16, 1
	v_bfe_u32 v42, v18, 16, 1
	v_add3_u32 v18, v18, v42, s84
	v_add3_u32 v19, v19, v41, s84
	v_add3_u32 v20, v20, v40, s84
	v_bfe_u32 v40, v33, 16, 1
	v_bfe_u32 v41, v38, 16, 1
	v_bfe_u32 v42, v39, 16, 1
	v_add3_u32 v42, v39, v42, s84
	v_add3_u32 v43, v38, v41, s84
	v_add3_u32 v33, v33, v40, s84
	global_load_dwordx4 v[38:41], v[22:23], off offset:448
	v_lshrrev_b32_e32 v35, 16, v35
	v_and_or_b32 v16, v16, s3, v35
	v_bfe_u32 v35, v21, 16, 1
	v_add3_u32 v21, v21, v35, s84
	v_bfe_u32 v35, v32, 16, 1
	v_add3_u32 v32, v32, v35, s84
	v_lshrrev_b32_e32 v32, 16, v32
	v_lshrrev_b32_e32 v22, 16, v33
	v_lshrrev_b32_e32 v23, 16, v43
	v_lshrrev_b32_e32 v33, 16, v42
	v_and_or_b32 v21, v21, s3, v33
	v_and_or_b32 v20, v20, s3, v23
	v_and_or_b32 v19, v19, s3, v22
	v_and_or_b32 v18, v18, s3, v32
	s_waitcnt vmcnt(2)
	v_lshlrev_b32_e32 v23, 16, v25
	v_lshlrev_b32_e32 v22, 16, v24
	v_and_b32_e32 v25, 0xffff0000, v25
	v_and_b32_e32 v24, 0xffff0000, v24
	v_lshlrev_b32_e32 v33, 16, v27
	v_lshlrev_b32_e32 v32, 16, v26
	v_and_b32_e32 v27, 0xffff0000, v27
	v_and_b32_e32 v26, 0xffff0000, v26
	v_pk_mul_f32 v[24:25], v[24:25], s[0:1] op_sel_hi:[1,0]
	v_pk_mul_f32 v[26:27], v[26:27], s[0:1] op_sel_hi:[1,0]
	v_pk_mul_f32 v[32:33], v[32:33], s[0:1] op_sel_hi:[1,0]
	v_bfe_u32 v35, v27, 16, 1
	v_bfe_u32 v42, v26, 16, 1
	v_bfe_u32 v43, v25, 16, 1
	v_bfe_u32 v44, v24, 16, 1
	v_pk_mul_f32 v[22:23], v[22:23], s[0:1] op_sel_hi:[1,0]
	v_add3_u32 v44, v24, v44, s84
	v_add3_u32 v43, v25, v43, s84
	v_add3_u32 v24, v26, v42, s84
	v_add3_u32 v25, v27, v35, s84
	v_bfe_u32 v35, v32, 16, 1
	v_bfe_u32 v42, v33, 16, 1
	v_bfe_u32 v26, v22, 16, 1
	v_bfe_u32 v27, v23, 16, 1
	v_add3_u32 v33, v33, v42, s84
	v_add3_u32 v32, v32, v35, s84
	v_add3_u32 v23, v23, v27, s84
	v_add3_u32 v22, v22, v26, s84
	v_lshrrev_b32_e32 v26, 16, v32
	v_lshrrev_b32_e32 v27, 16, v33
	v_and_or_b32 v25, v25, s3, v27
	v_and_or_b32 v24, v24, s3, v26
	v_lshrrev_b32_e32 v22, 16, v22
	v_lshrrev_b32_e32 v23, 16, v23
	v_and_or_b32 v23, v43, s3, v23
	v_and_or_b32 v22, v44, s3, v22
	s_waitcnt vmcnt(1)
; __device__ __forceinline__ u32x4 pack8(const float* f) { u32x4 o; o.x = pk2(f[0], f[1]); o.y = pk2(f[2], f[3]); o.z = pk2(f[4], f[5]); o.w = pk2(f[6], f[7]); return o; }
; __device__ __forceinline__ void phase_xattn(CArgs& A, int l, unsigned char* lds, int tid) {
;     ...
;         for (int ks = 0; ks < 8; ++ks) { float f[8]; unpack8(*(const u32x4*)(Q + row * DM + h * 256 + 32 * ks + 8 * g), f);
; #pragma unroll
;             for (int i = 0; i < 8; ++i) f[i] *= 0.0625f;
;             qf[ks] = __builtin_bit_cast(bf16x8, pack8(f)); }
;         f32x4 o[16];
; #pragma unroll
;         for (int i = 0; i < 16; ++i) o[i] = (f32x4){0.f, 0.f, 0.f, 0.f};
;         float m = -INFINITY, lsum = 0.f;
;         const int skey = tid >> 3, sdc = (tid & 7) * 32;
;         const bf16* kvbase = KV + ((size_t)b * NMEM + skey) * 4096 + l * 2048 + h * 256 + sdc;
;         u32x4 kr[4], vr[4];
; #pragma unroll
;         for (int i = 0; i < 4; ++i) { kr[i] = *(const u32x4*)(kvbase + i * 8); vr[i] = *(const u32x4*)(kvbase + 1024 + i * 8); }
	v_lshlrev_b32_e32 v27, 16, v29
	v_lshlrev_b32_e32 v26, 16, v28
	v_and_b32_e32 v29, 0xffff0000, v29
	v_and_b32_e32 v28, 0xffff0000, v28
	v_lshlrev_b32_e32 v33, 16, v31
	v_lshlrev_b32_e32 v32, 16, v30
	v_and_b32_e32 v31, 0xffff0000, v31
	v_and_b32_e32 v30, 0xffff0000, v30
	v_pk_mul_f32 v[28:29], v[28:29], s[0:1] op_sel_hi:[1,0]
	v_pk_mul_f32 v[30:31], v[30:31], s[0:1] op_sel_hi:[1,0]
	v_pk_mul_f32 v[32:33], v[32:33], s[0:1] op_sel_hi:[1,0]
	v_bfe_u32 v35, v31, 16, 1
	v_bfe_u32 v42, v30, 16, 1
	v_bfe_u32 v43, v29, 16, 1
	v_bfe_u32 v44, v28, 16, 1
	v_pk_mul_f32 v[26:27], v[26:27], s[0:1] op_sel_hi:[1,0]
	v_add3_u32 v44, v28, v44, s84
	v_add3_u32 v43, v29, v43, s84
	v_add3_u32 v28, v30, v42, s84
	v_add3_u32 v29, v31, v35, s84
	v_bfe_u32 v35, v32, 16, 1
	v_bfe_u32 v42, v33, 16, 1
	v_bfe_u32 v30, v26, 16, 1
	v_bfe_u32 v31, v27, 16, 1
	v_add3_u32 v33, v33, v42, s84
	v_add3_u32 v32, v32, v35, s84
	v_add3_u32 v27, v27, v31, s84
	v_add3_u32 v26, v26, v30, s84
	v_lshrrev_b32_e32 v30, 16, v32
	v_lshrrev_b32_e32 v31, 16, v33
	v_and_or_b32 v29, v29, s3, v31
	v_and_or_b32 v28, v28, s3, v30
	s_waitcnt vmcnt(0)
	v_lshlrev_b32_e32 v31, 16, v39
	v_lshlrev_b32_e32 v30, 16, v38
	v_and_b32_e32 v33, 0xffff0000, v39
	v_and_b32_e32 v32, 0xffff0000, v38
	v_lshlrev_b32_e32 v39, 16, v41
	v_lshlrev_b32_e32 v38, 16, v40
	v_and_b32_e32 v41, 0xffff0000, v41
	v_and_b32_e32 v40, 0xffff0000, v40
	v_lshrrev_b32_e32 v26, 16, v26
	v_lshrrev_b32_e32 v27, 16, v27
	v_pk_mul_f32 v[32:33], v[32:33], s[0:1] op_sel_hi:[1,0]
	v_pk_mul_f32 v[40:41], v[40:41], s[0:1] op_sel_hi:[1,0]
	v_and_or_b32 v27, v43, s3, v27
	v_and_or_b32 v26, v44, s3, v26
	v_pk_mul_f32 v[38:39], v[38:39], s[0:1] op_sel_hi:[1,0]
	v_bfe_u32 v35, v41, 16, 1
	v_bfe_u32 v42, v40, 16, 1
	v_bfe_u32 v43, v33, 16, 1
	v_bfe_u32 v44, v32, 16, 1
	v_pk_mul_f32 v[30:31], v[30:31], s[0:1] op_sel_hi:[1,0]
	v_add3_u32 v44, v32, v44, s84
	v_add3_u32 v43, v33, v43, s84
	v_add3_u32 v32, v40, v42, s84
	v_add3_u32 v33, v41, v35, s84
	v_bfe_u32 v41, v38, 16, 1
	v_bfe_u32 v42, v39, 16, 1
	v_bfe_u32 v35, v30, 16, 1
	v_add3_u32 v39, v39, v42, s84
	v_add3_u32 v38, v38, v41, s84
	v_add3_u32 v30, v30, v35, s84
	v_lshrrev_b32_e32 v35, 16, v38
	v_lshrrev_b32_e32 v38, 16, v39
	v_bfe_u32 v40, v31, 16, 1
	v_and_or_b32 v33, v33, s3, v38
	v_ashrrev_i32_e32 v38, 3, v1
	s_lshl_b64 s[0:1], s[4:5], 21
	v_add3_u32 v31, v31, v40, s84
	v_ashrrev_i32_e32 v39, 31, v38
	s_add_u32 s4, s9, s0
	v_lshrrev_b32_e32 v31, 16, v31
	s_addc_u32 s5, s10, s1
	v_lshlrev_b64 v[40:41], 13, v[38:39]
	v_and_or_b32 v31, v43, s3, v31
	v_lshl_add_u64 v[42:43], s[4:5], 0, v[40:41]
	v_and_or_b32 v32, v32, s3, v35
	v_lshl_add_u64 v[42:43], s[40:41], 1, v[42:43]
	v_lshlrev_b32_e32 v35, 6, v1
	v_lshl_add_u64 v[42:43], v[42:43], 0, s[14:15]
	v_and_b32_e32 v146, 0x1c0, v35
	v_lshl_add_u64 v[42:43], v[42:43], 0, v[146:147]
	global_load_dwordx4 v[98:101], v[42:43], off offset:48
	v_add_u32_e32 v39, 0, v34
	v_cndmask_b32_e32 v34, v167, v178, vcc
	v_cmp_lt_i32_e32 vcc, v179, v173
	s_movk_i32 s4, 0x220
	v_lshlrev_b32_e32 v151, 2, v34
	v_cndmask_b32_e32 v34, v167, v179, vcc
	v_mul_lo_u32 v35, v38, s4
	v_lshlrev_b32_e32 v147, 2, v34
	v_bfe_u32 v34, v1, 2, 2
	v_add_u32_e32 v154, 0, v35
	v_or_b32_e32 v34, v143, v34
	v_lshlrev_b32_e32 v35, 3, v1
	v_and_b32_e32 v35, 24, v35
	v_mul_u32_u24_e32 v34, 0x220, v34
	v_add3_u32 v152, 0, v35, v34
	v_lshl_add_u64 v[34:35], s[0:1], 0, v[40:41]
	s_lshl_b32 s0, s11, 5
	s_and_b32 s0, s0, 0x600
	v_lshrrev_b32_e32 v30, 16, v30
	v_mov_b32_e32 v38, v154
	v_or3_b32 v34, v34, s0, v37
	v_and_or_b32 v30, v44, s3, v30
	v_lshl_add_u64 v[148:149], s[42:43], 0, v[34:35]
	v_add_u32_e32 v155, v38, v146
	v_add_u32_e32 v153, v39, v36
	v_mov_b32_e32 v34, 0
	v_mov_b32_e32 v35, v130
	v_mov_b32_e32 v36, v130
	v_mov_b32_e32 v37, v130
	v_mov_b32_e32 v38, 0
	v_mov_b32_e32 v39, v130
	v_mov_b32_e32 v40, v130
	v_mov_b32_e32 v41, v130
	v_mov_b32_e32 v42, 0
	v_mov_b32_e32 v43, v130
	v_mov_b32_e32 v44, v130
	v_mov_b32_e32 v45, v130
	v_mov_b32_e32 v46, 0
	v_mov_b32_e32 v47, v130
	v_mov_b32_e32 v48, v130
	v_mov_b32_e32 v49, v130
	v_mov_b32_e32 v50, 0
	s_waitcnt vmcnt(0)
